# grid barriers: the first arriver of each XCD starts an L2 write-back before polling
# speedup vs baseline: 1.0137x; 1.0137x over previous
.LBB0_88:
	s_or_b64 exec, exec, s[6:7]
	v_cvt_f32_u32_e32 v4, v2
	s_waitcnt vmcnt(0)
	v_readfirstlane_b32 s4, v3
	v_sub_u32_e32 v3, 0, v2
	v_rcp_iflag_f32_e32 v4, v4
	v_add_u32_e32 v5, s4, v1
	v_mul_f32_e32 v4, 0x4f7ffffe, v4
	v_cvt_u32_f32_e32 v4, v4
	v_mul_lo_u32 v1, v3, v4
	v_mul_hi_u32 v1, v4, v1
	v_add_u32_e32 v1, v4, v1
	v_mul_hi_u32 v1, v5, v1
	v_mul_lo_u32 v3, v1, v2
	v_sub_u32_e32 v3, v5, v3
	v_add_u32_e32 v4, 1, v1
	v_cmp_ge_u32_e32 vcc, v3, v2
	s_nop 1
	v_cndmask_b32_e32 v1, v1, v4, vcc
	v_sub_u32_e32 v4, v3, v2
	v_cndmask_b32_e32 v3, v3, v4, vcc
	v_add_u32_e32 v4, 1, v1
	v_cmp_ge_u32_e32 vcc, v3, v2
	v_add_u32_e32 v3, 1, v5
	s_nop 0
	v_cndmask_b32_e32 v1, v1, v4, vcc
	v_mul_lo_u32 v4, v2, v1
	v_add_u32_e32 v2, v4, v2
	v_cmp_ne_u32_e32 vcc, v3, v2
	s_and_saveexec_b64 s[4:5], vcc
	s_xor_b64 s[4:5], exec, s[4:5]
	s_cbranch_execz .LBB0_102
	s_waitcnt lgkmcnt(0)
	v_add_u32_e32 v0, 1, v4
	v_cmp_eq_u32_e32 vcc, v3, v0
	s_cbranch_vccz .Lef_1
	buffer_wbl2 sc1
.Lef_1:
	v_mov_b32_e32 v0, 0x2000
	global_load_dword v0, v0, s[2:3] offset:1024 sc1
	s_add_u32 s8, s2, 0x2400
	s_addc_u32 s9, s3, 0
	s_waitcnt vmcnt(0)
	v_cmp_eq_u32_e32 vcc, v0, v1
	s_and_saveexec_b64 s[6:7], vcc
	s_cbranch_execz .LBB0_101
	s_mov_b32 s20, 1
	s_mov_b64 s[10:11], 0
	v_mov_b32_e32 v0, 0
	s_branch .LBB0_92

.Lef_4:
	v_mov_b32_e32 v0, 0x2000
	global_load_dword v0, v0, s[2:3] offset:1024 sc1
	s_add_u32 s8, s2, 0x2400
	s_addc_u32 s9, s3, 0
	s_waitcnt vmcnt(0)
	v_cmp_eq_u32_e32 vcc, v0, v1
	s_and_saveexec_b64 s[6:7], vcc
	s_cbranch_execz .LBB0_450
	s_mov_b32 s30, 1
	s_mov_b64 s[10:11], 0
	v_mov_b32_e32 v0, 0
	s_branch .LBB0_441

.Lef_5:
	v_mov_b32_e32 v0, 0x2000
	global_load_dword v0, v0, s[2:3] offset:1024 sc1
	s_add_u32 s8, s2, 0x2400
	s_addc_u32 s9, s3, 0
	s_waitcnt vmcnt(0)
	v_cmp_eq_u32_e32 vcc, v0, v1
	s_and_saveexec_b64 s[6:7], vcc
	s_cbranch_execz .LBB0_555
	s_mov_b32 s28, 1
	s_mov_b64 s[10:11], 0
	v_mov_b32_e32 v0, 0
	s_branch .LBB0_546
